# adds: background conversion share of the IN/UP barrier slots dealt only to the workgroups with one tile fewer
# speedup vs baseline: 1.0170x; 1.0012x over previous
; #define LAS __attribute__((address_space(3)))
; __device__ __forceinline__ void cv_background(Frame& F, const CvPtrs& P, int s) {
;     int tv = threadIdx.x; asm volatile("" : "+v"(tv));
;     const int w = __builtin_amdgcn_readfirstlane(tv >> 6) - 1, lane = tv & 63, nbw = F.G * (NWAVES - 1);
;     LAS float* scr = (LAS float*)(F.lds + RING_OFF + (w + 1) * 16384);
;     const int sh_ = cv_bg_share(s), hi = (sh_ + 1) * CV_BG_PER < CV_BG_TOTAL ? (sh_ + 1) * CV_BG_PER : CV_BG_TOTAL;
;     for (int j = sh_ * CV_BG_PER + F.vcu * (NWAVES - 1) + w; j < hi; j += nbw) {
;         if (j < BG_L0A) cv_dispatch(P, F.ws, F.out, 0, CV_BG0 + j, scr, lane);
;         else if (j < BG_L0A + BG_P_ITEMS) cv_p_item(F.ws, P.p + (size_t)M * PLE, j - BG_L0A, lane);
;         else if (j < BG_L1_AT) cv_dispatch(P, F.ws, F.out, 0, CV_BG0 + j - BG_P_ITEMS, scr, lane);
;         else { const int jj = j - BG_L1_AT; cv_dispatch(P, F.ws, F.out, 1, jj < CI_IN ? jj : (jj < CI_IN + CI_PL ? CV_NITEMS - CI_PL + (jj - CI_IN) : jj - CI_PL), scr, lane); }
;     }
.LBB0_801:
	s_add_i32 s1, s9, 0x6d6
	s_ashr_i32 s0, s8, 6
	s_min_u32 s6, s1, 0x3880
	s_mov_b32 s98, s34
	s_mov_b32 s99, s87
	s_cmpk_lg_u32 s87, 0x100
	s_cbranch_scc1 .Lbg_idx_done
	s_and_b32 s4, s34, 31
	s_lshr_b32 s5, s34, 5
	s_cmp_eq_u32 s90, 5
	s_cbranch_scc1 .Lbg_up
	s_cmp_eq_u32 s90, 1
	s_cbranch_scc1 .Lbg_in
	s_cmp_eq_u32 s90, 8
	s_cbranch_scc0 .Lbg_idx_done
.Lbg_in:
	s_cmp_lt_u32 s4, 16
	s_cbranch_scc1 .LBB0_1015
	s_sub_u32 s4, s4, 16
	s_lshl_b32 s4, s4, 3
	s_add_u32 s98, s4, s5
	s_movk_i32 s99, 0x80
	s_branch .Lbg_idx_done
.Lbg_up:
	s_lshl_b32 s4, s4, 3
	s_add_u32 s4, s4, s5
	s_cmpk_lt_u32 s4, 0xc2
	s_cbranch_scc1 .LBB0_1015
	s_sub_u32 s98, s4, 0xc2
	s_movk_i32 s99, 0x3e
.Lbg_idx_done:
	s_mul_i32 s1, s98, 7
	s_add_i32 s1, s1, s0
	s_add_i32 s1, s1, s9
	s_add_i32 s7, s1, -1
	s_cmp_ge_i32 s7, s6
	s_cbranch_scc1 .LBB0_1015
	v_and_b32_e32 v5, 7, v4
	v_readlane_b32 s4, v253, 20
	v_lshlrev_b32_e32 v2, 4, v5
	v_readlane_b32 s5, v253, 21
	s_lshl_b32 s1, s0, 14
	v_bfe_u32 v97, v4, 3, 3
	v_lshl_add_u64 v[52:53], s[4:5], 0, v[2:3]
	v_readlane_b32 s4, v253, 22
	v_readlane_b32 s5, v253, 23
	v_readlane_b32 s36, v251, 18
	s_add_i32 s1, s1, 0
	v_lshl_add_u64 v[54:55], s[4:5], 0, v[2:3]
	v_readlane_b32 s4, v253, 24
	v_readlane_b32 s5, v253, 25
	v_mul_u32_u24_e32 v5, 0x420, v5
	v_lshlrev_b32_e32 v6, 2, v97
	v_lshl_add_u64 v[56:57], s[4:5], 0, v[2:3]
	v_readlane_b32 s4, v251, 54
	v_readlane_b32 s5, v251, 55
	v_readlane_b32 s37, v251, 19
	v_readlane_b32 s38, v251, 20
	v_lshl_add_u64 v[58:59], s[4:5], 0, v[2:3]
	v_readlane_b32 s4, v253, 28
	v_readlane_b32 s5, v253, 29
	v_readlane_b32 s39, v251, 21
	v_readlane_b32 s40, v251, 22
	v_lshl_add_u64 v[60:61], s[4:5], 0, v[2:3]
	v_readlane_b32 s4, v253, 30
	v_readlane_b32 s5, v253, 31
	v_readlane_b32 s41, v251, 23
	v_readlane_b32 s42, v251, 24
	v_lshl_add_u64 v[64:65], s[4:5], 0, v[2:3]
	v_readlane_b32 s4, v253, 34
	v_readlane_b32 s5, v253, 35
	v_readlane_b32 s43, v251, 25
	v_readlane_b32 s44, v251, 26
	v_lshl_add_u64 v[66:67], s[4:5], 0, v[2:3]
	v_readlane_b32 s4, v253, 36
	v_readlane_b32 s5, v253, 37
	v_readlane_b32 s45, v251, 27
	v_readlane_b32 s46, v251, 28
	v_lshl_add_u64 v[68:69], s[4:5], 0, v[2:3]
	v_readlane_b32 s4, v253, 38
	v_readlane_b32 s5, v253, 39
	v_readlane_b32 s47, v251, 29
	v_readlane_b32 s48, v251, 30
	v_lshl_add_u64 v[70:71], s[4:5], 0, v[2:3]
	v_readlane_b32 s4, v253, 40
	v_readlane_b32 s5, v253, 41
	v_readlane_b32 s49, v251, 31
	v_readlane_b32 s50, v251, 32
	v_lshl_add_u64 v[72:73], s[4:5], 0, v[2:3]
	v_readlane_b32 s4, v253, 42
	v_readlane_b32 s5, v253, 43
	v_readlane_b32 s51, v251, 33
	s_add_i32 s0, s9, s0
	v_lshl_add_u64 v[74:75], s[4:5], 0, v[2:3]
	v_readlane_b32 s4, v253, 44
	v_readlane_b32 s5, v253, 45
	v_add_u32_e32 v99, s1, v2
	v_add3_u32 v103, s1, v5, v6
	v_lshl_add_u64 v[76:77], s[4:5], 0, v[2:3]
	v_readlane_b32 s4, v253, 46
	v_readlane_b32 s5, v253, 47
	v_lshl_add_u64 v[42:43], s[48:49], 0, v[2:3]
	v_lshl_add_u64 v[44:45], s[44:45], 0, v[2:3]
	v_lshl_add_u64 v[78:79], s[4:5], 0, v[2:3]
	v_readlane_b32 s4, v253, 48
	v_readlane_b32 s5, v253, 49
	v_lshl_add_u64 v[46:47], s[42:43], 0, v[2:3]
	v_lshl_add_u64 v[48:49], s[38:39], 0, v[2:3]
	v_lshl_add_u64 v[80:81], s[4:5], 0, v[2:3]
	v_readlane_b32 s4, v251, 58
	v_readlane_b32 s5, v251, 59
	v_readlane_b32 s36, v251, 2
	s_mul_i32 s1, s98, 0x3800
	v_lshl_add_u64 v[82:83], s[4:5], 0, v[2:3]
	v_readlane_b32 s4, v251, 62
	v_readlane_b32 s5, v251, 63
	s_lshl_b32 s0, s0, 11
	v_and_b32_e32 v4, 63, v4
	v_lshl_add_u64 v[84:85], s[4:5], 0, v[2:3]
	v_readlane_b32 s4, v252, 0
	v_readlane_b32 s5, v252, 1
	v_readlane_b32 s42, v251, 8
	v_readlane_b32 s43, v251, 9
	v_lshl_add_u64 v[86:87], s[4:5], 0, v[2:3]
	v_readlane_b32 s4, v252, 2
	v_readlane_b32 s5, v252, 3
	s_add_i32 s0, s1, s0
	v_lshl_add_u64 v[36:37], s[92:93], 0, v[2:3]
	v_lshl_add_u64 v[38:39], s[68:69], 0, v[2:3]
	v_lshl_add_u64 v[40:41], s[62:63], 0, v[2:3]
	v_lshl_add_u64 v[50:51], s[42:43], 0, v[2:3]
	v_lshl_add_u64 v[62:63], s[58:59], 0, v[2:3]
	v_lshl_add_u64 v[88:89], s[4:5], 0, v[2:3]
	v_lshl_add_u64 v[90:91], s[84:85], 0, v[2:3]
	v_lshlrev_b32_e32 v2, 3, v4
	s_add_i32 s18, s0, 0xff87f800
	v_readlane_b32 s0, v253, 63
	v_lshl_add_u64 v[92:93], s[74:75], 0, v[2:3]
	v_lshlrev_b32_e32 v2, 4, v4
	v_readlane_b32 s1, v254, 0
	v_mul_u32_u24_e32 v105, 0x84, v97
	v_or_b32_e32 v107, 8, v97
	v_or_b32_e32 v109, 16, v97
	v_or_b32_e32 v112, 24, v97
	v_lshl_add_u64 v[94:95], s[0:1], 0, v[2:3]
	v_readlane_b32 s37, v251, 3
	v_readlane_b32 s38, v251, 4
	v_readlane_b32 s39, v251, 5
	v_readlane_b32 s40, v251, 6
	v_readlane_b32 s41, v251, 7
	v_readlane_b32 s44, v251, 10
	v_readlane_b32 s45, v251, 11
	v_readlane_b32 s46, v251, 12
	v_readlane_b32 s47, v251, 13
	v_readlane_b32 s48, v251, 14
	v_readlane_b32 s49, v251, 15
	v_readlane_b32 s50, v251, 16
	v_readlane_b32 s51, v251, 17
	s_branch .LBB0_805

; #define LAS __attribute__((address_space(3)))
; __device__ __forceinline__ void cv_background(Frame& F, const CvPtrs& P, int s) {
;     ...
;     const int w = __builtin_amdgcn_readfirstlane(tv >> 6) - 1, lane = tv & 63, nbw = F.G * (NWAVES - 1);
;     LAS float* scr = (LAS float*)(F.lds + RING_OFF + (w + 1) * 16384);
;     const int sh_ = cv_bg_share(s), hi = (sh_ + 1) * CV_BG_PER < CV_BG_TOTAL ? (sh_ + 1) * CV_BG_PER : CV_BG_TOTAL;
;     for (int j = sh_ * CV_BG_PER + F.vcu * (NWAVES - 1) + w; j < hi; j += nbw) {
.LBB0_804:
	s_mul_i32 s0, s99, 7
	s_add_i32 s7, s7, s0
	s_mul_i32 s0, s99, 0x3800
	s_add_i32 s18, s18, s0
	s_cmp_lt_i32 s7, s6
	s_cbranch_scc0 .LBB0_1015
